# adds: HGRN2 chunk-loop top wait no longer drains the readout stores (vmcnt(2); explicit drains on the no-store and preheader edges)
# baseline (speedup 1.0000x reference)
.LBB0_254:
	v_cndmask_b32_e64 v0, v130, v127, s[4:5]
	v_cndmask_b32_e64 v1, v128, v129, s[4:5]
	v_readlane_b32 s6, v255, 13
	v_cndmask_b32_e64 v6, v134, v131, s[4:5]
	v_cndmask_b32_e64 v7, v132, v133, s[4:5]
	v_readlane_b32 s8, v255, 15
	v_add_u32_e32 v0, s86, v0
	v_add_u32_e32 v1, s85, v1
	v_readlane_b32 s7, v255, 14
	v_add_u32_e32 v6, s86, v6
	v_add_u32_e32 v7, s85, v7
	v_readlane_b32 s9, v255, 16
	v_cndmask_b32_e64 v0, v1, v0, s[6:7]
	v_mad_i64_i32 v[0:1], s[6:7], v0, s19, v[106:107]
	v_cndmask_b32_e64 v6, v7, v6, s[8:9]
	v_mad_i64_i32 v[6:7], s[8:9], v6, s19, v[106:107]
	v_add_co_u32_e32 v2, vcc, 0x1000, v0
	v_cndmask_b32_e64 v12, v138, v135, s[4:5]
	v_cndmask_b32_e64 v13, v136, v137, s[4:5]
	v_readlane_b32 s8, v255, 17
	v_addc_co_u32_e32 v3, vcc, 0, v1, vcc
	v_add_u32_e32 v12, s86, v12
	v_add_u32_e32 v13, s85, v13
	v_readlane_b32 s9, v255, 18
	v_add_co_u32_e32 v8, vcc, s76, v6
	s_nop 0
	v_cndmask_b32_e64 v12, v13, v12, s[8:9]
	v_addc_co_u32_e32 v9, vcc, 0, v7, vcc
	v_mad_i64_i32 v[12:13], s[8:9], v12, s19, v[106:107]
	s_lshl_b64 s[6:7], s[72:73], 1
	v_add_co_u32_e32 v14, vcc, s76, v12
	v_lshl_add_u64 v[4:5], v[0:1], 0, s[6:7]
	v_lshl_add_u64 v[10:11], v[6:7], 0, s[6:7]
	v_addc_co_u32_e32 v15, vcc, 0, v13, vcc
	global_load_dword v192, v[0:1], off
	global_load_dword v161, v[2:3], off
	global_load_dword v171, v[4:5], off
	global_load_dword v119, v[6:7], off
	global_load_dword v162, v[8:9], off
	global_load_dword v169, v[10:11], off
	global_load_dword v118, v[12:13], off
	global_load_dword v163, v[14:15], off
	v_cndmask_b32_e64 v2, v142, v139, s[4:5]
	v_cndmask_b32_e64 v3, v140, v141, s[4:5]
	v_readlane_b32 s8, v255, 19
	v_add_u32_e32 v2, s86, v2
	v_add_u32_e32 v3, s85, v3
	v_readlane_b32 s9, v255, 20
	v_cndmask_b32_e64 v8, v146, v143, s[4:5]
	v_cndmask_b32_e64 v9, v144, v145, s[4:5]
	v_cndmask_b32_e64 v2, v3, v2, s[8:9]
	v_mad_i64_i32 v[2:3], s[8:9], v2, s19, v[106:107]
	v_readlane_b32 s8, v255, 21
	v_add_u32_e32 v8, s86, v8
	v_add_u32_e32 v9, s85, v9
	v_readlane_b32 s9, v255, 22
	v_cndmask_b32_e64 v14, v150, v147, s[4:5]
	v_cndmask_b32_e64 v15, v148, v149, s[4:5]
	v_cndmask_b32_e64 v8, v9, v8, s[8:9]
	v_mad_i64_i32 v[8:9], s[8:9], v8, s19, v[106:107]
	v_readlane_b32 s8, v255, 23
	v_add_co_u32_e32 v4, vcc, s76, v2
	v_add_u32_e32 v14, s86, v14
	v_add_u32_e32 v15, s85, v15
	v_readlane_b32 s9, v255, 24
	v_addc_co_u32_e32 v5, vcc, 0, v3, vcc
	s_nop 0
	v_cndmask_b32_e64 v14, v15, v14, s[8:9]
	v_lshl_add_u64 v[0:1], v[12:13], 0, s[6:7]
	v_add_co_u32_e32 v10, vcc, s76, v8
	v_mad_i64_i32 v[14:15], s[8:9], v14, s19, v[106:107]
	v_lshl_add_u64 v[6:7], v[2:3], 0, s[6:7]
	v_addc_co_u32_e32 v11, vcc, 0, v9, vcc
	v_lshl_add_u64 v[12:13], v[8:9], 0, s[6:7]
	global_load_dword v174, v[0:1], off
	global_load_dword v191, v[2:3], off
	global_load_dword v164, v[4:5], off
	global_load_dword v172, v[6:7], off
	global_load_dword v120, v[8:9], off
	global_load_dword v165, v[10:11], off
	global_load_dword v170, v[12:13], off
	global_load_dword v121, v[14:15], off
	v_cndmask_b32_e64 v4, v154, v151, s[4:5]
	v_cndmask_b32_e64 v5, v152, v153, s[4:5]
	v_readlane_b32 s8, v255, 25
	v_add_u32_e32 v4, s86, v4
	v_add_u32_e32 v5, s85, v5
	v_readlane_b32 s9, v255, 26
	v_add_co_u32_e32 v0, vcc, s76, v14
	s_nop 0
	v_cndmask_b32_e64 v4, v5, v4, s[8:9]
	v_mad_i64_i32 v[4:5], s[8:9], v4, s19, v[106:107]
	v_cndmask_b32_e64 v10, v158, v155, s[4:5]
	v_cndmask_b32_e64 v11, v156, v157, s[4:5]
	v_readlane_b32 s8, v255, 27
	v_addc_co_u32_e32 v1, vcc, 0, v15, vcc
	v_add_u32_e32 v10, s86, v10
	v_add_u32_e32 v11, s85, v11
	v_readlane_b32 s9, v255, 28
	v_add_co_u32_e32 v6, vcc, s76, v4
	s_nop 0
	v_cndmask_b32_e64 v10, v11, v10, s[8:9]
	v_addc_co_u32_e32 v7, vcc, 0, v5, vcc
	v_mad_i64_i32 v[10:11], s[8:9], v10, s19, v[106:107]
	v_add_co_u32_e32 v12, vcc, 0x1000, v10
	v_lshl_add_u64 v[2:3], v[14:15], 0, s[6:7]
	v_lshl_add_u64 v[8:9], v[4:5], 0, s[6:7]
	v_addc_co_u32_e32 v13, vcc, 0, v11, vcc
	v_lshl_add_u64 v[14:15], v[10:11], 0, s[6:7]
	global_load_dword v166, v[0:1], off
	global_load_dword v175, v[2:3], off
	global_load_dword v193, v[4:5], off
	global_load_dword v167, v[6:7], off
	global_load_dword v173, v[8:9], off
	global_load_dword v190, v[10:11], off
	global_load_dword v168, v[12:13], off
	global_load_dword v176, v[14:15], off
	s_xor_b64 s[6:7], s[4:5], -1
	s_and_b64 s[8:9], s[4:5], exec
	s_movk_i32 s8, 0xb000
	v_mov_b32_e32 v76, 0
	s_mov_b32 s87, 0
	s_cselect_b32 s88, 0, -1
	s_cselect_b32 s89, 0x5000, s8
	s_lshl_b32 s72, s72, 1
	s_mov_b32 s90, 64
	v_mov_b32_e32 v77, v76
	v_mov_b32_e32 v78, v76
	v_mov_b32_e32 v79, v76
	v_mov_b32_e32 v72, v76
	v_mov_b32_e32 v73, v76
	v_mov_b32_e32 v74, v76
	v_mov_b32_e32 v75, v76
	v_mov_b32_e32 v68, v76
	v_mov_b32_e32 v69, v76
	v_mov_b32_e32 v70, v76
	v_mov_b32_e32 v71, v76
	v_mov_b32_e32 v64, v76
	v_mov_b32_e32 v65, v76
	v_mov_b32_e32 v66, v76
	v_mov_b32_e32 v67, v76
	v_mov_b32_e32 v60, v76
	v_mov_b32_e32 v61, v76
	v_mov_b32_e32 v62, v76
	v_mov_b32_e32 v63, v76
	v_mov_b32_e32 v56, v76
	v_mov_b32_e32 v57, v76
	v_mov_b32_e32 v58, v76
	v_mov_b32_e32 v59, v76
	v_mov_b32_e32 v52, v76
	v_mov_b32_e32 v53, v76
	v_mov_b32_e32 v54, v76
	v_mov_b32_e32 v55, v76
	v_mov_b32_e32 v80, v76
	v_mov_b32_e32 v81, v76
	v_mov_b32_e32 v82, v76
	v_mov_b32_e32 v83, v76
	s_waitcnt vmcnt(0)
	s_branch .LBB0_256

.LBB0_256:
	s_waitcnt vmcnt(2)
	v_lshlrev_b32_e32 v2, 16, v171
	v_and_b32_e32 v3, 0xffff0000, v171
	v_mul_f32_e64 v0, |v2|, s78
	v_exp_f32_e32 v0, v0
	v_mul_f32_e64 v1, |v3|, s78
	v_exp_f32_e32 v1, v1
	v_and_b32_e32 v5, 0xffff0000, v169
	v_add_f32_e32 v4, 1.0, v0
	v_rcp_f32_e32 v40, v4
	v_add_f32_e32 v4, 1.0, v1
	v_rcp_f32_e32 v41, v4
	v_lshlrev_b32_e32 v4, 16, v169
	v_cmp_le_f32_e64 s[44:45], 0, v4
	v_cmp_le_f32_e64 s[46:47], 0, v5
	v_pk_mul_f32 v[42:43], v[0:1], v[40:41]
	v_mul_f32_e64 v0, |v4|, s78
	v_exp_f32_e32 v0, v0
	v_mul_f32_e64 v1, |v5|, s78
	v_exp_f32_e32 v1, v1
	v_lshlrev_b32_e32 v4, 16, v174
	v_add_f32_e32 v6, 1.0, v0
	v_rcp_f32_e32 v46, v6
	v_add_f32_e32 v6, 1.0, v1
	v_rcp_f32_e32 v47, v6
	v_and_b32_e32 v5, 0xffff0000, v174
	v_and_b32_e32 v7, 0xffff0000, v172
	v_and_b32_e32 v9, 0xffff0000, v170
	v_pk_mul_f32 v[48:49], v[0:1], v[46:47]
	v_mul_f32_e64 v0, |v4|, s78
	v_exp_f32_e32 v0, v0
	v_mul_f32_e64 v1, |v5|, s78
	v_exp_f32_e32 v1, v1
	v_and_b32_e32 v11, 0xffff0000, v175
	v_add_f32_e32 v6, 1.0, v0
	v_rcp_f32_e32 v50, v6
	v_add_f32_e32 v6, 1.0, v1
	v_rcp_f32_e32 v51, v6
	v_lshlrev_b32_e32 v6, 16, v172
	v_and_b32_e32 v13, 0xffff0000, v173
	v_and_b32_e32 v15, 0xffff0000, v176
	v_pk_mul_f32 v[84:85], v[0:1], v[50:51]
	v_mul_f32_e64 v0, |v6|, s78
	v_exp_f32_e32 v0, v0
	v_mul_f32_e64 v1, |v7|, s78
	v_exp_f32_e32 v1, v1
	v_cmp_le_f32_e64 s[40:41], 0, v2
	v_add_f32_e32 v8, 1.0, v0
	v_rcp_f32_e32 v86, v8
	v_add_f32_e32 v8, 1.0, v1
	v_rcp_f32_e32 v87, v8
	v_lshlrev_b32_e32 v8, 16, v170
	v_cndmask_b32_e64 v2, v42, v40, s[40:41]
	v_cmp_le_f32_e64 s[42:43], 0, v3
	v_pk_mul_f32 v[88:89], v[0:1], v[86:87]
	v_mul_f32_e64 v0, |v8|, s78
	v_exp_f32_e32 v0, v0
	v_mul_f32_e64 v1, |v9|, s78
	v_exp_f32_e32 v1, v1
	v_cndmask_b32_e64 v3, v43, v41, s[42:43]
	v_add_f32_e32 v10, 1.0, v0
	v_rcp_f32_e32 v90, v10
	v_add_f32_e32 v10, 1.0, v1
	v_rcp_f32_e32 v91, v10
	v_lshlrev_b32_e32 v10, 16, v175
	v_add_f32_e32 v2, 0, v2
	v_cmp_le_f32_e64 s[38:39], 0, v15
	v_pk_mul_f32 v[92:93], v[0:1], v[90:91]
	v_mul_f32_e64 v0, |v10|, s78
	v_exp_f32_e32 v0, v0
	v_mul_f32_e64 v1, |v11|, s78
	v_exp_f32_e32 v1, v1
	v_mov_b32_e32 v16, v122
	v_add_f32_e32 v12, 1.0, v0
	v_rcp_f32_e32 v94, v12
	v_add_f32_e32 v12, 1.0, v1
	v_rcp_f32_e32 v95, v12
	v_lshlrev_b32_e32 v12, 16, v173
	v_mov_b32_e32 v100, v124
	v_mov_b32_e32 v177, v123
	v_pk_mul_f32 v[96:97], v[0:1], v[94:95]
	v_mul_f32_e64 v0, |v12|, s78
	v_exp_f32_e32 v0, v0
	v_mul_f32_e64 v1, |v13|, s78
	v_exp_f32_e32 v1, v1
	v_max_f32_e32 v44, 0xda24260, v2
	v_add_f32_e32 v14, 1.0, v0
	v_rcp_f32_e32 v98, v14
	v_add_f32_e32 v14, 1.0, v1
	v_rcp_f32_e32 v99, v14
	v_lshlrev_b32_e32 v14, 16, v176
	v_cmp_le_f32_e64 s[36:37], 0, v14
	v_add_f32_e32 v2, 0, v3
	v_pk_mul_f32 v[108:109], v[0:1], v[98:99]
	v_mul_f32_e64 v0, |v14|, s78
	v_exp_f32_e32 v0, v0
	v_mul_f32_e64 v1, |v15|, s78
	v_exp_f32_e32 v1, v1
	v_cmp_le_f32_e64 s[48:49], 0, v4
	v_add_f32_e32 v17, 1.0, v0
	v_rcp_f32_e32 v28, v17
	v_add_f32_e32 v17, 1.0, v1
	v_rcp_f32_e32 v29, v17
	v_cmp_le_f32_e64 s[50:51], 0, v5
	v_cmp_le_f32_e64 s[52:53], 0, v6
	v_cmp_le_f32_e64 s[54:55], 0, v7
	v_pk_mul_f32 v[30:31], v[0:1], v[28:29]
	v_cmp_le_f32_e64 s[56:57], 0, v8
	v_cndmask_b32_e64 v0, v30, v28, s[36:37]
	v_cmp_le_f32_e64 s[58:59], 0, v9
	v_cmp_le_f32_e64 s[62:63], 0, v10
	v_cmp_le_f32_e64 s[64:65], 0, v11
	v_cmp_le_f32_e64 s[66:67], 0, v12
	v_cmp_le_f32_e64 s[68:69], 0, v13
	v_cndmask_b32_e64 v1, v31, v29, s[38:39]
	v_add_f32_e32 v0, 0, v0
	s_waitcnt lgkmcnt(0)
	s_barrier
	v_max_f32_e32 v45, 0xda24260, v2
	v_cndmask_b32_e64 v2, v48, v46, s[44:45]
	v_cndmask_b32_e64 v3, v49, v47, s[46:47]
	v_cndmask_b32_e64 v4, v84, v50, s[48:49]
	v_cndmask_b32_e64 v5, v85, v51, s[50:51]
	v_cndmask_b32_e64 v6, v88, v86, s[52:53]
	v_cndmask_b32_e64 v7, v89, v87, s[54:55]
	v_cndmask_b32_e64 v8, v92, v90, s[56:57]
	v_cndmask_b32_e64 v9, v93, v91, s[58:59]
	v_cndmask_b32_e64 v10, v96, v94, s[62:63]
	v_cndmask_b32_e64 v11, v97, v95, s[64:65]
	v_cndmask_b32_e64 v12, v108, v98, s[66:67]
	v_cndmask_b32_e64 v13, v109, v99, s[68:69]
	v_max_f32_e32 v32, 0xda24260, v0
	v_add_f32_e32 v0, 0, v1
	v_add_f32_e32 v2, 0, v2
	v_add_f32_e32 v3, 0, v3
	v_add_f32_e32 v4, 0, v4
	v_add_f32_e32 v5, 0, v5
	v_add_f32_e32 v6, 0, v6
	v_add_f32_e32 v7, 0, v7
	v_add_f32_e32 v8, 0, v8
	v_add_f32_e32 v9, 0, v9
	v_add_f32_e32 v10, 0, v10
	v_add_f32_e32 v11, 0, v11
	v_add_f32_e32 v12, 0, v12
	v_add_f32_e32 v13, 0, v13
	v_max_f32_e32 v33, 0xda24260, v0
	v_cndmask_b32_e64 v0, 0, 1, s[70:71]
	v_max_f32_e32 v2, 0xda24260, v2
	v_max_f32_e32 v3, 0xda24260, v3
	v_max_f32_e32 v4, 0xda24260, v4
	v_max_f32_e32 v5, 0xda24260, v5
	v_max_f32_e32 v6, 0xda24260, v6
	v_max_f32_e32 v7, 0xda24260, v7
	v_max_f32_e32 v8, 0xda24260, v8
	v_max_f32_e32 v9, 0xda24260, v9
	v_max_f32_e32 v10, 0xda24260, v10
	v_max_f32_e32 v11, 0xda24260, v11
	v_max_f32_e32 v12, 0xda24260, v12
	v_max_f32_e32 v13, 0xda24260, v13
	v_cmp_ne_u32_e64 s[60:61], 1, v0
	s_andn2_b64 vcc, exec, s[70:71]
	s_mov_b64 s[8:9], -1
	s_cbranch_vccnz .LBB0_258
	v_mul_f32_e32 v0, v12, v32
	v_max_f32_e32 v34, 0xda24260, v0
	v_mul_f32_e32 v0, v13, v33
	v_max_f32_e32 v35, 0xda24260, v0
	v_mul_f32_e32 v0, v10, v34
	v_max_f32_e32 v36, 0xda24260, v0
	v_mul_f32_e32 v0, v11, v35
	v_max_f32_e32 v37, 0xda24260, v0
	v_mul_f32_e32 v0, v8, v36
	v_max_f32_e32 v110, 0xda24260, v0
	v_mul_f32_e32 v0, v9, v37
	v_max_f32_e32 v111, 0xda24260, v0
	v_mul_f32_e32 v0, v6, v110
	v_max_f32_e32 v112, 0xda24260, v0
	v_mul_f32_e32 v0, v7, v111
	v_max_f32_e32 v113, 0xda24260, v0
	v_mul_f32_e32 v0, v4, v112
	v_max_f32_e32 v114, 0xda24260, v0
	v_mul_f32_e32 v0, v5, v113
	v_max_f32_e32 v115, 0xda24260, v0
	v_mul_f32_e32 v0, v2, v114
	v_max_f32_e32 v15, 0xda24260, v0
	v_mul_f32_e32 v0, v3, v115
	v_max_f32_e32 v14, 0xda24260, v0
	v_mul_f32_e32 v0, v44, v15
	v_mul_f32_e32 v1, v45, v14
	v_max_f32_e32 v0, 0xda24260, v0
	v_max_f32_e32 v1, 0xda24260, v1
	s_mov_b64 s[8:9], 0

.Lhg0_nostore:
	s_waitcnt vmcnt(0)
	s_branch .LBB0_255

.LBB0_2344:
	v_readlane_b32 s36, v254, 21
	v_readlane_b32 s38, v254, 23
	v_readlane_b32 s39, v254, 24
	s_mov_b64 s[18:19], s[38:39]
	v_readlane_b32 s38, v255, 15
	v_or_b32_e32 v102, s7, v166
	s_or_b32 s38, s7, 0x1000
	v_lshl_add_u64 v[0:1], v[102:103], 2, s[18:19]
	v_or_b32_e32 v102, s38, v166
	v_lshl_add_u64 v[2:3], v[102:103], 2, s[18:19]
	global_load_dwordx2 v[0:1], v[0:1], off
	v_cndmask_b32_e64 v4, v135, v132, s[74:75]
	global_load_dwordx2 v[2:3], v[2:3], off
	v_cndmask_b32_e64 v5, v133, v134, s[74:75]
	v_readlane_b32 s18, v255, 17
	v_add_u32_e32 v4, s17, v4
	v_add_u32_e32 v5, s16, v5
	v_readlane_b32 s19, v255, 18
	v_cndmask_b32_e64 v6, v139, v136, s[74:75]
	v_cndmask_b32_e64 v7, v137, v138, s[74:75]
	v_cndmask_b32_e64 v4, v5, v4, s[18:19]
	v_readlane_b32 s18, v255, 19
	v_add_u32_e32 v6, s17, v6
	v_add_u32_e32 v7, s16, v7
	v_readlane_b32 s19, v255, 20
	v_cndmask_b32_e64 v8, v143, v140, s[74:75]
	v_cndmask_b32_e64 v9, v141, v142, s[74:75]
	v_cndmask_b32_e64 v6, v7, v6, s[18:19]
	v_readlane_b32 s18, v255, 21
	v_add_u32_e32 v8, s17, v8
	v_add_u32_e32 v9, s16, v9
	v_readlane_b32 s19, v255, 22
	v_cndmask_b32_e64 v10, v147, v144, s[74:75]
	v_cndmask_b32_e64 v11, v145, v146, s[74:75]
	v_cndmask_b32_e64 v8, v9, v8, s[18:19]
	v_readlane_b32 s18, v255, 23
	v_add_u32_e32 v10, s17, v10
	v_add_u32_e32 v11, s16, v11
	v_readlane_b32 s19, v255, 24
	s_movk_i32 s8, 0x5000
	s_movk_i32 s7, 0x1000
	v_cndmask_b32_e64 v10, v11, v10, s[18:19]
	v_mad_i64_i32 v[4:5], s[18:19], v4, s8, v[108:109]
	v_add_co_u32_e32 v12, vcc, s7, v4
	v_mad_i64_i32 v[6:7], s[18:19], v6, s8, v[108:109]
	s_nop 0
	v_addc_co_u32_e32 v13, vcc, 0, v5, vcc
	v_add_co_u32_e32 v16, vcc, s7, v6
	v_readlane_b32 s39, v255, 16
	v_mad_i64_i32 v[8:9], s[18:19], v8, s8, v[108:109]
	v_addc_co_u32_e32 v17, vcc, 0, v7, vcc
	s_lshl_b64 s[0:1], s[38:39], 1
	v_add_co_u32_e32 v20, vcc, s7, v8
	v_lshl_add_u64 v[14:15], v[4:5], 0, s[0:1]
	v_lshl_add_u64 v[18:19], v[6:7], 0, s[0:1]
	v_addc_co_u32_e32 v21, vcc, 0, v9, vcc
	global_load_dword v126, v[4:5], off
	global_load_dword v167, v[12:13], off
	global_load_dword v176, v[14:15], off
	global_load_dword v125, v[6:7], off
	global_load_dword v168, v[16:17], off
	global_load_dword v175, v[18:19], off
	global_load_dword v124, v[8:9], off
	global_load_dword v169, v[20:21], off
	v_lshl_add_u64 v[22:23], v[8:9], 0, s[0:1]
	v_readlane_b32 s37, v254, 22
	v_mad_i64_i32 v[10:11], s[18:19], v10, s8, v[108:109]
	v_cndmask_b32_e64 v16, v155, v152, s[74:75]
	v_cndmask_b32_e64 v17, v153, v154, s[74:75]
	v_add_u32_e32 v16, s17, v16
	v_add_u32_e32 v17, s16, v17
	v_mov_b32_e32 v76, 0
	v_mov_b32_e32 v77, v76
	v_mov_b32_e32 v78, v76
	v_mov_b32_e32 v79, v76
	v_mov_b32_e32 v72, v76
	v_mov_b32_e32 v73, v76
	v_mov_b32_e32 v74, v76
	v_mov_b32_e32 v75, v76
	v_mov_b32_e32 v68, v76
	v_mov_b32_e32 v69, v76
	v_mov_b32_e32 v70, v76
	v_mov_b32_e32 v71, v76
	v_mov_b32_e32 v64, v76
	v_mov_b32_e32 v65, v76
	v_mov_b32_e32 v66, v76
	v_mov_b32_e32 v67, v76
	v_mov_b32_e32 v60, v76
	s_waitcnt vmcnt(0)
	v_max_f32_e32 v24, v1, v1
	v_max_f32_e32 v25, v0, v0
	v_max_f32_e32 v26, v3, v3
	v_max_f32_e32 v27, v2, v2
	v_max_f32_e32 v24, v24, v26
	v_max_f32_e32 v25, v25, v27
	v_sub_f32_e32 v1, v1, v24
	v_sub_f32_e32 v3, v3, v24
	v_sub_f32_e32 v2, v2, v25
	v_sub_f32_e32 v0, v0, v25
	v_mul_f32_e32 v1, 0x3fb8aa3b, v1
	v_mul_f32_e32 v3, 0x3fb8aa3b, v3
	v_mul_f32_e32 v2, 0x3fb8aa3b, v2
	v_mul_f32_e32 v0, 0x3fb8aa3b, v0
	v_exp_f32_e32 v1, v1
	v_exp_f32_e32 v3, v3
	v_exp_f32_e32 v2, v2
	v_exp_f32_e32 v0, v0
	v_mov_b32_e32 v61, v76
	v_mov_b32_e32 v62, v76
	v_mov_b32_e32 v63, v76
	v_pk_add_f32 v[0:1], v[0:1], v[2:3]
	v_mov_b32_e32 v56, v76
	v_div_scale_f32 v4, s[18:19], v1, v1, v3
	v_div_scale_f32 v6, s[18:19], v0, v0, v2
	v_rcp_f32_e32 v7, v4
	v_rcp_f32_e32 v8, v6
	v_div_scale_f32 v5, vcc, v3, v1, v3
	v_fma_f32 v12, -v4, v7, 1.0
	v_fma_f32 v13, -v6, v8, 1.0
	v_fmac_f32_e32 v7, v12, v7
	v_div_scale_f32 v9, s[36:37], v2, v0, v2
	v_fmac_f32_e32 v8, v13, v8
	v_mul_f32_e32 v12, v5, v7
	v_mul_f32_e32 v13, v9, v8
	v_fma_f32 v14, -v4, v12, v5
	v_fma_f32 v15, -v6, v13, v9
	v_fmac_f32_e32 v12, v14, v7
	v_fmac_f32_e32 v13, v15, v8
	v_fma_f32 v4, -v4, v12, v5
	v_fma_f32 v5, -v6, v13, v9
	v_div_fmas_f32 v20, v4, v7, v12
	s_mov_b64 vcc, s[36:37]
	v_div_fmas_f32 v21, v5, v8, v13
	v_cndmask_b32_e64 v8, v151, v148, s[74:75]
	v_cndmask_b32_e64 v9, v149, v150, s[74:75]
	v_readlane_b32 s18, v255, 25
	v_add_u32_e32 v8, s17, v8
	v_add_u32_e32 v9, s16, v9
	v_readlane_b32 s19, v255, 26
	v_add_co_u32_e32 v4, vcc, s7, v10
	s_nop 0
	v_cndmask_b32_e64 v8, v9, v8, s[18:19]
	v_mad_i64_i32 v[8:9], s[18:19], v8, s8, v[108:109]
	v_readlane_b32 s18, v255, 27
	v_readlane_b32 s19, v255, 28
	v_addc_co_u32_e32 v5, vcc, 0, v11, vcc
	s_nop 0
	v_cndmask_b32_e64 v16, v17, v16, s[18:19]
	v_add_co_u32_e32 v12, vcc, s7, v8
	v_mad_i64_i32 v[16:17], s[18:19], v16, s8, v[108:109]
	v_lshl_add_u64 v[6:7], v[10:11], 0, s[0:1]
	v_addc_co_u32_e32 v13, vcc, 0, v9, vcc
	v_lshl_add_u64 v[14:15], v[8:9], 0, s[0:1]
	global_load_dword v180, v[22:23], off
	global_load_dword v198, v[10:11], off
	global_load_dword v170, v[4:5], off
	global_load_dword v178, v[6:7], off
	global_load_dword v127, v[8:9], off
	global_load_dword v171, v[12:13], off
	global_load_dword v177, v[14:15], off
	global_load_dword v197, v[16:17], off
	v_cndmask_b32_e64 v8, v159, v156, s[74:75]
	v_cndmask_b32_e64 v9, v157, v158, s[74:75]
	v_readlane_b32 s18, v255, 31
	v_add_u32_e32 v8, s17, v8
	v_add_u32_e32 v9, s16, v9
	v_readlane_b32 s19, v255, 32
	v_add_co_u32_e32 v4, vcc, s7, v16
	s_nop 0
	v_cndmask_b32_e64 v8, v9, v8, s[18:19]
	v_mad_i64_i32 v[8:9], s[18:19], v8, s8, v[108:109]
	v_cndmask_b32_e64 v14, v163, v160, s[74:75]
	v_cndmask_b32_e64 v15, v161, v162, s[74:75]
	v_readlane_b32 s18, v255, 5
	v_addc_co_u32_e32 v5, vcc, 0, v17, vcc
	v_add_u32_e32 v14, s17, v14
	v_add_u32_e32 v15, s16, v15
	v_readlane_b32 s19, v255, 6
	v_add_co_u32_e32 v10, vcc, s7, v8
	s_nop 0
	v_cndmask_b32_e64 v14, v15, v14, s[18:19]
	v_addc_co_u32_e32 v11, vcc, 0, v9, vcc
	v_mad_i64_i32 v[14:15], s[18:19], v14, s8, v[108:109]
	v_lshl_add_u64 v[6:7], v[16:17], 0, s[0:1]
	v_add_co_u32_e32 v16, vcc, s7, v14
	v_lshl_add_u64 v[12:13], v[8:9], 0, s[0:1]
	s_nop 0
	v_addc_co_u32_e32 v17, vcc, 0, v15, vcc
	v_lshl_add_u64 v[18:19], v[14:15], 0, s[0:1]
	global_load_dword v172, v[4:5], off
	global_load_dword v181, v[6:7], off
	global_load_dword v199, v[8:9], off
	global_load_dword v173, v[10:11], off
	global_load_dword v179, v[12:13], off
	global_load_dword v196, v[14:15], off
	global_load_dword v174, v[16:17], off
	global_load_dword v182, v[18:19], off
	s_xor_b64 s[0:1], s[74:75], -1
	v_div_fixup_f32 v111, v20, v1, v3
	v_div_fixup_f32 v110, v21, v0, v2
	s_and_b64 s[18:19], s[74:75], exec
	s_movk_i32 s7, 0xb000
	v_writelane_b32 v255, s38, 15
	v_pk_add_f32 v[112:113], v[110:111], 1.0 op_sel_hi:[1,0] neg_lo:[1,0] neg_hi:[1,0]
	s_cselect_b32 s78, 0, -1
	s_cselect_b32 s79, 0x5000, s7
	v_writelane_b32 v255, s39, 16
	s_lshl_b32 s82, s38, 1
	s_mov_b32 s18, 64
	s_mov_b32 s19, 0
	s_mov_b32 s7, 0
	v_mov_b32_e32 v57, v76
	v_mov_b32_e32 v58, v76
	v_mov_b32_e32 v59, v76
	v_mov_b32_e32 v52, v76
	v_mov_b32_e32 v53, v76
	v_mov_b32_e32 v54, v76
	v_mov_b32_e32 v55, v76
	v_mov_b32_e32 v80, v76
	v_mov_b32_e32 v81, v76
	v_mov_b32_e32 v82, v76
	v_mov_b32_e32 v83, v76
	v_readlane_b32 s40, v254, 25
	v_readlane_b32 s41, v254, 26
	v_readlane_b32 s42, v254, 27
	v_readlane_b32 s43, v254, 28
	v_readlane_b32 s44, v254, 29
	v_readlane_b32 s45, v254, 30
	v_readlane_b32 s46, v254, 31
	v_readlane_b32 s47, v254, 32
	v_readlane_b32 s48, v254, 33
	v_readlane_b32 s49, v254, 34
	v_readlane_b32 s50, v254, 35
	v_readlane_b32 s51, v254, 36
	s_waitcnt vmcnt(0)
	s_branch .LBB0_2346

.LBB0_2346:
	v_lshlrev_b32_e32 v2, 16, v176
	v_and_b32_e32 v3, 0xffff0000, v176
	v_mul_f32_e64 v0, |v2|, s10
	v_exp_f32_e32 v0, v0
	v_mul_f32_e64 v1, |v3|, s10
	v_exp_f32_e32 v1, v1
	v_and_b32_e32 v5, 0xffff0000, v175
	v_add_f32_e32 v4, 1.0, v0
	v_rcp_f32_e32 v42, v4
	v_add_f32_e32 v4, 1.0, v1
	v_rcp_f32_e32 v43, v4
	v_lshlrev_b32_e32 v4, 16, v175
	v_cmp_le_f32_e64 s[46:47], 0, v4
	v_cmp_le_f32_e64 s[48:49], 0, v5
	v_pk_mul_f32 v[44:45], v[0:1], v[42:43]
	v_mul_f32_e64 v0, |v4|, s10
	v_exp_f32_e32 v0, v0
	v_mul_f32_e64 v1, |v5|, s10
	v_exp_f32_e32 v1, v1
	s_waitcnt vmcnt(15)
	v_lshlrev_b32_e32 v4, 16, v180
	v_add_f32_e32 v6, 1.0, v0
	v_rcp_f32_e32 v46, v6
	v_add_f32_e32 v6, 1.0, v1
	v_rcp_f32_e32 v47, v6
	v_and_b32_e32 v5, 0xffff0000, v180
	s_waitcnt vmcnt(12)
	v_and_b32_e32 v7, 0xffff0000, v178
	s_waitcnt vmcnt(9)
	v_and_b32_e32 v9, 0xffff0000, v177
	v_pk_mul_f32 v[48:49], v[0:1], v[46:47]
	v_mul_f32_e64 v0, |v4|, s10
	v_exp_f32_e32 v0, v0
	v_mul_f32_e64 v1, |v5|, s10
	v_exp_f32_e32 v1, v1
	s_waitcnt vmcnt(6)
	v_and_b32_e32 v11, 0xffff0000, v181
	v_add_f32_e32 v6, 1.0, v0
	v_rcp_f32_e32 v50, v6
	v_add_f32_e32 v6, 1.0, v1
	v_rcp_f32_e32 v51, v6
	v_lshlrev_b32_e32 v6, 16, v178
	s_waitcnt vmcnt(3)
	v_and_b32_e32 v13, 0xffff0000, v179
	s_waitcnt vmcnt(2)
	v_and_b32_e32 v15, 0xffff0000, v182
	v_pk_mul_f32 v[84:85], v[0:1], v[50:51]
	v_mul_f32_e64 v0, |v6|, s10
	v_exp_f32_e32 v0, v0
	v_mul_f32_e64 v1, |v7|, s10
	v_exp_f32_e32 v1, v1
	v_cmp_le_f32_e64 s[42:43], 0, v2
	v_add_f32_e32 v8, 1.0, v0
	v_rcp_f32_e32 v86, v8
	v_add_f32_e32 v8, 1.0, v1
	v_rcp_f32_e32 v87, v8
	v_lshlrev_b32_e32 v8, 16, v177
	v_cndmask_b32_e64 v2, v44, v42, s[42:43]
	v_cmp_le_f32_e64 s[44:45], 0, v3
	v_pk_mul_f32 v[88:89], v[0:1], v[86:87]
	v_mul_f32_e64 v0, |v8|, s10
	v_exp_f32_e32 v0, v0
	v_mul_f32_e64 v1, |v9|, s10
	v_exp_f32_e32 v1, v1
	v_cndmask_b32_e64 v3, v45, v43, s[44:45]
	v_add_f32_e32 v10, 1.0, v0
	v_rcp_f32_e32 v90, v10
	v_add_f32_e32 v10, 1.0, v1
	v_rcp_f32_e32 v91, v10
	v_lshlrev_b32_e32 v10, 16, v181
	v_fma_f32 v2, v112, v2, v110
	v_cmp_le_f32_e64 s[40:41], 0, v15
	v_pk_mul_f32 v[92:93], v[0:1], v[90:91]
	v_mul_f32_e64 v0, |v10|, s10
	v_exp_f32_e32 v0, v0
	v_mul_f32_e64 v1, |v11|, s10
	v_exp_f32_e32 v1, v1
	v_mov_b32_e32 v16, v101
	v_add_f32_e32 v12, 1.0, v0
	v_rcp_f32_e32 v94, v12
	v_add_f32_e32 v12, 1.0, v1
	v_rcp_f32_e32 v95, v12
	v_lshlrev_b32_e32 v12, 16, v179
	v_mov_b32_e32 v102, v129
	v_mov_b32_e32 v183, v128
	v_pk_mul_f32 v[96:97], v[0:1], v[94:95]
	v_mul_f32_e64 v0, |v12|, s10
	v_exp_f32_e32 v0, v0
	v_mul_f32_e64 v1, |v13|, s10
	v_exp_f32_e32 v1, v1
	v_max_f32_e32 v40, 0xda24260, v2
	v_add_f32_e32 v14, 1.0, v0
	v_rcp_f32_e32 v98, v14
	v_add_f32_e32 v14, 1.0, v1
	v_rcp_f32_e32 v99, v14
	v_lshlrev_b32_e32 v14, 16, v182
	v_cmp_le_f32_e64 s[38:39], 0, v14
	v_fma_f32 v2, v113, v3, v111
	v_pk_mul_f32 v[114:115], v[0:1], v[98:99]
	v_mul_f32_e64 v0, |v14|, s10
	v_exp_f32_e32 v0, v0
	v_mul_f32_e64 v1, |v15|, s10
	v_exp_f32_e32 v1, v1
	v_cmp_le_f32_e64 s[50:51], 0, v4
	v_add_f32_e32 v17, 1.0, v0
	v_rcp_f32_e32 v28, v17
	v_add_f32_e32 v17, 1.0, v1
	v_rcp_f32_e32 v29, v17
	v_cmp_le_f32_e64 s[52:53], 0, v5
	v_cmp_le_f32_e64 s[54:55], 0, v6
	v_cmp_le_f32_e64 s[56:57], 0, v7
	v_pk_mul_f32 v[30:31], v[0:1], v[28:29]
	v_cmp_le_f32_e64 s[58:59], 0, v8
	v_cndmask_b32_e64 v0, v30, v28, s[38:39]
	v_cmp_le_f32_e64 s[60:61], 0, v9
	v_cmp_le_f32_e64 s[64:65], 0, v10
	v_cmp_le_f32_e64 s[66:67], 0, v11
	v_cmp_le_f32_e64 s[68:69], 0, v12
	v_cmp_le_f32_e64 s[70:71], 0, v13
	v_cndmask_b32_e64 v1, v31, v29, s[40:41]
	v_fma_f32 v0, v112, v0, v110
	s_waitcnt lgkmcnt(0)
	s_barrier
	v_max_f32_e32 v41, 0xda24260, v2
	v_cndmask_b32_e64 v2, v48, v46, s[46:47]
	v_cndmask_b32_e64 v3, v49, v47, s[48:49]
	v_cndmask_b32_e64 v4, v84, v50, s[50:51]
	v_cndmask_b32_e64 v5, v85, v51, s[52:53]
	v_cndmask_b32_e64 v6, v88, v86, s[54:55]
	v_cndmask_b32_e64 v7, v89, v87, s[56:57]
	v_cndmask_b32_e64 v8, v92, v90, s[58:59]
	v_cndmask_b32_e64 v9, v93, v91, s[60:61]
	v_cndmask_b32_e64 v10, v96, v94, s[64:65]
	v_cndmask_b32_e64 v11, v97, v95, s[66:67]
	v_cndmask_b32_e64 v12, v114, v98, s[68:69]
	v_cndmask_b32_e64 v13, v115, v99, s[70:71]
	v_max_f32_e32 v32, 0xda24260, v0
	v_fma_f32 v0, v113, v1, v111
	v_fma_f32 v2, v112, v2, v110
	v_fma_f32 v3, v113, v3, v111
	v_fma_f32 v4, v112, v4, v110
	v_fma_f32 v5, v113, v5, v111
	v_fma_f32 v6, v112, v6, v110
	v_fma_f32 v7, v113, v7, v111
	v_fma_f32 v8, v112, v8, v110
	v_fma_f32 v9, v113, v9, v111
	v_fma_f32 v10, v112, v10, v110
	v_fma_f32 v11, v113, v11, v111
	v_fma_f32 v12, v112, v12, v110
	v_fma_f32 v13, v113, v13, v111
	v_max_f32_e32 v33, 0xda24260, v0
	v_cndmask_b32_e64 v0, 0, 1, s[76:77]
	v_max_f32_e32 v2, 0xda24260, v2
	v_max_f32_e32 v3, 0xda24260, v3
	v_max_f32_e32 v4, 0xda24260, v4
	v_max_f32_e32 v5, 0xda24260, v5
	v_max_f32_e32 v6, 0xda24260, v6
	v_max_f32_e32 v7, 0xda24260, v7
	v_max_f32_e32 v8, 0xda24260, v8
	v_max_f32_e32 v9, 0xda24260, v9
	v_max_f32_e32 v10, 0xda24260, v10
	v_max_f32_e32 v11, 0xda24260, v11
	v_max_f32_e32 v12, 0xda24260, v12
	v_max_f32_e32 v13, 0xda24260, v13
	v_cmp_ne_u32_e64 s[62:63], 1, v0
	s_andn2_b64 vcc, exec, s[76:77]
	s_mov_b64 s[36:37], -1
	s_cbranch_vccnz .LBB0_2348
	v_mul_f32_e32 v0, v12, v32
	v_max_f32_e32 v34, 0xda24260, v0
	v_mul_f32_e32 v0, v13, v33
	v_max_f32_e32 v35, 0xda24260, v0
	v_mul_f32_e32 v0, v10, v34
	v_max_f32_e32 v36, 0xda24260, v0
	v_mul_f32_e32 v0, v11, v35
	v_max_f32_e32 v37, 0xda24260, v0
	v_mul_f32_e32 v0, v8, v36
	v_max_f32_e32 v116, 0xda24260, v0
	v_mul_f32_e32 v0, v9, v37
	v_max_f32_e32 v117, 0xda24260, v0
	v_mul_f32_e32 v0, v6, v116
	v_max_f32_e32 v118, 0xda24260, v0
	v_mul_f32_e32 v0, v7, v117
	v_max_f32_e32 v119, 0xda24260, v0
	v_mul_f32_e32 v0, v4, v118
	v_max_f32_e32 v120, 0xda24260, v0
	v_mul_f32_e32 v0, v5, v119
	v_max_f32_e32 v121, 0xda24260, v0
	v_mul_f32_e32 v0, v2, v120
	v_max_f32_e32 v15, 0xda24260, v0
	v_mul_f32_e32 v0, v3, v121
	v_max_f32_e32 v14, 0xda24260, v0
	v_mul_f32_e32 v0, v40, v15
	v_mul_f32_e32 v1, v41, v14
	v_max_f32_e32 v0, 0xda24260, v0
	v_max_f32_e32 v1, 0xda24260, v1
	s_mov_b64 s[36:37], 0
